# fox loop also as two staggered roles with straight-line steady-state interval bodies
# speedup vs baseline: 1.0173x; 1.0091x over previous
; __device__ __forceinline__ s16x4 vtr(ldsp p) { return __builtin_bit_cast(s16x4, __builtin_amdgcn_ds_read_tr16_b64_v4i16((LAS v4i16_t*)p)); }
; template <bool DIFF>
; __device__ __forceinline__ void attn_unit(const AttnP& A, int b, int h, int qi, ldsp lds) {
;     ...
;     for (int kt = kt0; kt < nt; ++kt) {
;         if (kt + 1 < nt) LOAD_TILE(kt + 1);
;         if (64 * kt <= qmax_w) {
;             ldsp Kb = lds + (kt & 1) * STAGE; ldsp Vb = Kb + 64 * KP;
;             bf16x8 kf[8]; bf16x8 ka0, ka1, qa; f32x16 s0, s1;
;     ...
;             QK_BLOCK();
;             s16x4 vlo[8], vhi[8];
; #pragma unroll
;             for (int t = 0; t < 2; ++t)
; #pragma unroll
;                 for (int j = 0; j < 4; ++j) { vlo[t * 4 + j] = vtr(Vb + trb + (16 * j) * VP + t * 64); vhi[t * 4 + j] = vtr(Vb + trb + (16 * j + 8) * VP + t * 64); }
.Lfa_top:
	s_cmp_le_i32 s99, s93
	s_cbranch_scc1 .Lfa_gen
	s_cmp_ge_i32 s99, s95
	s_cbranch_scc1 .Lfa_gen
.Lfa_s_top:
	s_bitcmp1_b32 s99, 0
	s_cselect_b32 s74, 0x5500, 0
	s_sub_i32 s75, 0x5500, s74
	v_add_u32_e32 v169, s74, v150
	v_add_u32_e32 v0, s74, v164
	v_add_u32_e32 v168, s75, v161
	ds_read_b64_tr_b16 v[106:107], v168 offset:9216
	ds_read_b64_tr_b16 v[108:109], v168 offset:10752
	ds_read_b64_tr_b16 v[110:111], v168 offset:9280
	ds_read_b64_tr_b16 v[112:113], v168 offset:10816
	ds_read_b64_tr_b16 v[116:117], v168 offset:12288
	ds_read_b64_tr_b16 v[118:119], v168 offset:13824
	ds_read_b64_tr_b16 v[120:121], v168 offset:12352
	ds_read_b64_tr_b16 v[122:123], v168 offset:13888
	ds_read_b64_tr_b16 v[124:125], v168 offset:15360
	ds_read_b64_tr_b16 v[126:127], v168 offset:16896
	ds_read_b64_tr_b16 v[128:129], v168 offset:15424
	ds_read_b64_tr_b16 v[130:131], v168 offset:16960
	ds_read_b64_tr_b16 v[132:133], v168 offset:18432
	ds_read_b64_tr_b16 v[134:135], v168 offset:19968
	ds_read_b64_tr_b16 v[136:137], v168 offset:18496
	ds_read_b64_tr_b16 v[138:139], v168 offset:20032
	v_mov_b32_e32 v248, s97
	ds_read_b32 v248, v248
	ds_read_b128 v[170:173], v169
	ds_read_b128 v[244:247], v169 offset:4608
	s_waitcnt lgkmcnt(15)
	v_mfma_f32_32x32x16_bf16 v[18:33], v[106:109], v[66:69], v[18:33]
	ds_read_b128 v[106:109], v169 offset:32
	s_waitcnt lgkmcnt(15)
	v_mfma_f32_32x32x16_bf16 v[2:17], v[110:113], v[66:69], v[2:17]
	ds_read_b128 v[110:113], v169 offset:4640
	s_waitcnt lgkmcnt(15)
	v_mfma_f32_32x32x16_bf16 v[18:33], v[116:119], v[70:73], v[18:33]
	ds_read_b128 v[116:119], v169 offset:64
	s_waitcnt lgkmcnt(14)
	v_mfma_f32_32x32x16_bf16 v[2:17], v[120:123], v[70:73], v[2:17]
	ds_read_b128 v[120:123], v169 offset:4672
	s_waitcnt lgkmcnt(13)
	v_mfma_f32_32x32x16_bf16 v[18:33], v[124:127], v[50:53], v[18:33]
	ds_read_b128 v[124:127], v169 offset:96
	s_waitcnt lgkmcnt(12)
	v_mfma_f32_32x32x16_bf16 v[2:17], v[128:131], v[50:53], v[2:17]
	ds_read_b128 v[128:131], v169 offset:4704
	s_waitcnt lgkmcnt(11)
	v_mfma_f32_32x32x16_bf16 v[18:33], v[132:135], v[54:57], v[18:33]
	ds_read_b128 v[132:135], v0 offset:128
	s_waitcnt lgkmcnt(10)
	v_mfma_f32_32x32x16_bf16 v[2:17], v[136:139], v[54:57], v[2:17]
	ds_read_b128 v[136:139], v0 offset:4736
	s_waitcnt lgkmcnt(9)
	v_mfma_f32_32x32x16_bf16 v[66:81], v[170:173], v[90:93], v[34:49]
	s_waitcnt lgkmcnt(8)
	v_mfma_f32_32x32x16_bf16 v[50:65], v[244:247], v[90:93], v[34:49]
	v_sub_f32_e32 v249, v160, v248
	v_cvt_pk_bf16_f32 v162, v249, 0
	v_lshlrev_b32_e32 v162, 16, v162
	s_waitcnt lgkmcnt(7)
	v_mfma_f32_32x32x16_bf16 v[66:81], v[106:109], v[82:85], v[66:81]
	s_waitcnt lgkmcnt(6)
	v_mfma_f32_32x32x16_bf16 v[50:65], v[110:113], v[82:85], v[50:65]
	v_sub_f32_e32 v249, v249, v162
	v_cvt_pk_bf16_f32 v163, v249, 0
	v_and_b32_e32 v157, 0xffff, v163
	v_lshlrev_b32_e32 v163, 16, v163
	s_waitcnt lgkmcnt(5)
	v_mfma_f32_32x32x16_bf16 v[66:81], v[116:119], v[86:89], v[66:81]
	s_waitcnt lgkmcnt(4)
	v_mfma_f32_32x32x16_bf16 v[50:65], v[120:123], v[86:89], v[50:65]
	v_sub_f32_e32 v249, v249, v163
	v_cvt_pk_bf16_f32 v249, v249, 0
	v_or_b32_e32 v162, 0x3f80, v162
	v_lshl_or_b32 v249, v249, 16, v157
	v_cndmask_b32_e64 v140, 0, v114, s[46:47]
	v_cndmask_b32_e64 v142, 0, v249, s[46:47]
	v_cndmask_b32_e64 v141, 0, v162, s[46:47]
	v_mov_b32_e32 v143, v1
	s_waitcnt lgkmcnt(3)
	v_mfma_f32_32x32x16_bf16 v[66:81], v[124:127], v[94:97], v[66:81]
	s_waitcnt lgkmcnt(2)
	v_mfma_f32_32x32x16_bf16 v[50:65], v[128:131], v[94:97], v[50:65]
	s_waitcnt lgkmcnt(1)
	v_mfma_f32_32x32x16_bf16 v[66:81], v[132:135], v[140:143], v[66:81]
	s_waitcnt lgkmcnt(0)
	v_mfma_f32_32x32x16_bf16 v[50:65], v[136:139], v[140:143], v[50:65]
	s_waitcnt vmcnt(0)
	v_add_u32_e32 v115, s75, v156
	ds_write_b128 v115, v[98:101]
	s_and_saveexec_b64 s[0:1], s[44:45]
	v_xor_b32_e32 v248, 0x80000000, v155
	v_cvt_pk_bf16_f32 v248, v248, 0
	v_lshlrev_b32_e32 v249, 16, v248
	v_sub_f32_e64 v249, -v155, v249
	v_cvt_pk_bf16_f32 v162, v249, 0
	v_lshlrev_b32_e32 v162, 16, v162
	v_sub_f32_e32 v249, v249, v162
	v_cvt_pk_bf16_f32 v249, v249, 0
	v_and_or_b32 v112, v248, s83, v162
	v_and_or_b32 v113, v249, s83, 1.0
	v_mov_b32_e32 v115, v1
	v_add_u32_e32 v248, s75, v159
	ds_write_b128 v248, v[112:115] offset:128
	s_mov_b64 exec, s[0:1]
	v_add_u32_e32 v115, s74, v158
	ds_write_b128 v115, v[102:105] offset:9216
	global_load_dwordx4 v[102:105], v[250:251], off
	v_lshl_add_u64 v[250:251], v[250:251], 0, s[26:27]
	global_load_dwordx4 v[98:101], v[152:153], off
	v_lshl_add_u64 v[152:153], v[152:153], 0, s[26:27]
	s_and_saveexec_b64 s[0:1], s[44:45]
	global_load_dword v155, v[252:253], off
	s_mov_b64 exec, s[0:1]
	s_mov_b64 s[0:1], 0x800
	v_lshl_add_u64 v[252:253], v[252:253], 0, s[0:1]
	v_exp_f32_e32 v106, v66
	v_exp_f32_e32 v124, v50
	v_exp_f32_e32 v107, v67
	v_exp_f32_e32 v125, v51
	v_add_f32_e32 v166, 0, v106
	v_add_f32_e32 v167, 0, v124
	v_exp_f32_e32 v108, v68
	v_exp_f32_e32 v126, v52
	v_add_f32_e32 v166, v107, v166
	v_add_f32_e32 v167, v125, v167
	v_exp_f32_e32 v109, v69
	v_exp_f32_e32 v127, v53
	v_add_f32_e32 v166, v108, v166
	v_add_f32_e32 v167, v126, v167
	v_exp_f32_e32 v110, v70
	v_exp_f32_e32 v128, v54
	v_add_f32_e32 v166, v109, v166
	v_add_f32_e32 v167, v127, v167
	v_exp_f32_e32 v111, v71
	v_exp_f32_e32 v129, v55
	v_add_f32_e32 v166, v110, v166
	v_add_f32_e32 v167, v128, v167
	v_exp_f32_e32 v112, v72
	v_exp_f32_e32 v130, v56
	v_add_f32_e32 v166, v111, v166
	v_add_f32_e32 v167, v129, v167
	v_exp_f32_e32 v113, v73
	v_exp_f32_e32 v131, v57
	v_add_f32_e32 v166, v112, v166
	v_add_f32_e32 v167, v130, v167
	v_exp_f32_e32 v116, v74
	v_exp_f32_e32 v132, v58
	v_add_f32_e32 v166, v113, v166
	v_add_f32_e32 v167, v131, v167
	v_exp_f32_e32 v117, v75
	v_exp_f32_e32 v133, v59
	v_add_f32_e32 v166, v116, v166
	v_add_f32_e32 v167, v132, v167
	v_exp_f32_e32 v118, v76
	v_exp_f32_e32 v134, v60
	v_add_f32_e32 v166, v117, v166
	v_add_f32_e32 v167, v133, v167
	v_exp_f32_e32 v119, v77
	v_exp_f32_e32 v135, v61
	v_add_f32_e32 v166, v118, v166
	v_add_f32_e32 v167, v134, v167
	v_exp_f32_e32 v120, v78
	v_exp_f32_e32 v136, v62
	v_add_f32_e32 v166, v119, v166
	v_add_f32_e32 v167, v135, v167
	v_exp_f32_e32 v121, v79
	v_exp_f32_e32 v137, v63
	v_add_f32_e32 v166, v120, v166
	v_add_f32_e32 v167, v136, v167
	v_exp_f32_e32 v122, v80
	v_exp_f32_e32 v138, v64
	v_add_f32_e32 v166, v121, v166
	v_add_f32_e32 v167, v137, v167
	v_exp_f32_e32 v123, v81
	v_exp_f32_e32 v139, v65
	v_add_f32_e32 v166, v122, v166
	v_add_f32_e32 v167, v138, v167
	s_nop 0
	v_add_f32_e32 v166, v123, v166
	v_add_f32_e32 v167, v139, v167
	v_add_f32_e32 v141, v166, v167
	v_cmp_lt_f32_e32 vcc, s85, v141
	s_cbranch_vccnz .Lfa_s_slow
; __device__ __forceinline__ unsigned cvtpk(float lo, float hi) { f32x2 v = {lo, hi}; bf16x2_t b = __builtin_convertvector(v, bf16x2_t); return __builtin_bit_cast(unsigned, b); }
; template <bool DIFF>
; __device__ __forceinline__ void attn_unit(const AttnP& A, int b, int h, int qi, ldsp lds) {
;     ...
;             l_run += psa + psb;
;     ...
;             bf16x8 pw[4];
; #pragma unroll
;             for (int j = 0; j < 4; ++j) {
;                 u32x4 pk;
;                 if (j < 2) { const int rb = 8 * (j & 1); pk.x = cvtpk(s0[rb], s0[rb + 1]); pk.y = cvtpk(s0[rb + 2], s0[rb + 3]); pk.z = cvtpk(s0[rb + 4], s0[rb + 5]); pk.w = cvtpk(s0[rb + 6], s0[rb + 7]); }
;                 else { const int rb = 8 * (j & 1); pk.x = cvtpk(s1[rb], s1[rb + 1]); pk.y = cvtpk(s1[rb + 2], s1[rb + 3]); pk.z = cvtpk(s1[rb + 4], s1[rb + 5]); pk.w = cvtpk(s1[rb + 6], s1[rb + 7]); }
;                 pw[j] = __builtin_bit_cast(bf16x8, pk);
;             }
;     ...
;         if (kt + 1 < nt) STORE_TILE((kt + 1) & 1);
;         __syncthreads();
	v_cvt_pk_bf16_f32 v66, v106, v107
	v_cvt_pk_bf16_f32 v67, v108, v109
	v_cvt_pk_bf16_f32 v68, v110, v111
	v_cvt_pk_bf16_f32 v69, v112, v113
	v_cvt_pk_bf16_f32 v70, v116, v117
	v_cvt_pk_bf16_f32 v71, v118, v119
	v_cvt_pk_bf16_f32 v72, v120, v121
	v_cvt_pk_bf16_f32 v73, v122, v123
	v_cvt_pk_bf16_f32 v50, v124, v125
	v_cvt_pk_bf16_f32 v51, v126, v127
	v_cvt_pk_bf16_f32 v52, v128, v129
	v_cvt_pk_bf16_f32 v53, v130, v131
	v_cvt_pk_bf16_f32 v54, v132, v133
	v_cvt_pk_bf16_f32 v55, v134, v135
	v_cvt_pk_bf16_f32 v56, v136, v137
	v_cvt_pk_bf16_f32 v57, v138, v139
	v_add_f32_e32 v154, v141, v154
	s_waitcnt lgkmcnt(0)
	s_barrier
	s_add_i32 s99, s99, 1
	s_add_i32 s94, s94, 1
	s_add_i32 s97, s97, 4
	s_add_i32 s98, s98, 64
	s_add_i32 s0, s95, -1
	s_cmp_le_i32 s99, s0
	s_cbranch_scc1 .Lfa_s_top

; __device__ __forceinline__ s16x4 vtr(ldsp p) { return __builtin_bit_cast(s16x4, __builtin_amdgcn_ds_read_tr16_b64_v4i16((LAS v4i16_t*)p)); }
; #define MASK_BLOCK() do { if (kt == 0 || kt >= diag0) { \
;             _Pragma("unroll") for (int r = 0; r < 16; ++r) { const int kpp = 64 * kt + crow(r, hi); \
;                 if (kpp < 48 || kpp > q_pp) s0[r] = -INFINITY; \
;                 if (kpp + 32 < 48 || kpp + 32 > q_pp) s1[r] = -INFINITY; } } } while (0)
; #define EXPSUM_BLOCK() do { psa = 0.f; psb = 0.f; \
;             _Pragma("unroll") for (int r = 0; r < 16; ++r) { s0[r] = __builtin_amdgcn_exp2f(s0[r]); s1[r] = __builtin_amdgcn_exp2f(s1[r]); psa += s0[r]; asm("" : "+v"(psa)); psb += s1[r]; asm("" : "+v"(psb)); } } while (0)
; template <bool DIFF>
; __device__ __forceinline__ void attn_unit(const AttnP& A, int b, int h, int qi, ldsp lds) {
;     ...
;             QK_BLOCK();
;             s16x4 vlo[8], vhi[8];
; #pragma unroll
;             for (int t = 0; t < 2; ++t)
; #pragma unroll
;                 for (int j = 0; j < 4; ++j) { vlo[t * 4 + j] = vtr(Vb + trb + (16 * j) * VP + t * 64); vhi[t * 4 + j] = vtr(Vb + trb + (16 * j + 8) * VP + t * 64); }
;             __builtin_amdgcn_sched_barrier(0);
;             MASK_BLOCK();
;             bool full = (kt == kt0);
;             float psa, psb;
;             if (!full) {
;                 EXPSUM_BLOCK();
;                 if (__any(psa + psb > 1.0e18f)) { full = true; QK_BLOCK();
; #pragma unroll
;                     for (int t = 0; t < 2; ++t)
; #pragma unroll
;                         for (int j = 0; j < 4; ++j) { vlo[t * 4 + j] = vtr(Vb + trb + (16 * j) * VP + t * 64); vhi[t * 4 + j] = vtr(Vb + trb + (16 * j + 8) * VP + t * 64); }
;                     MASK_BLOCK(); }
;             }
.Lfa_s_slow:
	s_mov_b64 s[48:49], 0
	s_branch .Lfx6_full
.Lfb_top:
	s_add_i32 s0, s93, 2
	s_cmp_lt_i32 s99, s0
	s_cbranch_scc1 .Lfb_gen
	s_cmp_gt_i32 s99, s95
	s_cbranch_scc1 .Lfb_gen
.Lfb_s_top:
	s_bitcmp1_b32 s99, 0
	s_cselect_b32 s74, 0x5500, 0
	s_sub_i32 s75, 0x5500, s74
	v_exp_f32_e32 v106, v66
	v_exp_f32_e32 v124, v50
	v_exp_f32_e32 v107, v67
	v_exp_f32_e32 v125, v51
	v_add_f32_e32 v166, 0, v106
	v_add_f32_e32 v167, 0, v124
	v_exp_f32_e32 v108, v68
	v_exp_f32_e32 v126, v52
	v_add_f32_e32 v166, v107, v166
	v_add_f32_e32 v167, v125, v167
	v_exp_f32_e32 v109, v69
	v_exp_f32_e32 v127, v53
	v_add_f32_e32 v166, v108, v166
	v_add_f32_e32 v167, v126, v167
	v_exp_f32_e32 v110, v70
	v_exp_f32_e32 v128, v54
	v_add_f32_e32 v166, v109, v166
	v_add_f32_e32 v167, v127, v167
	v_exp_f32_e32 v111, v71
	v_exp_f32_e32 v129, v55
	v_add_f32_e32 v166, v110, v166
	v_add_f32_e32 v167, v128, v167
	v_exp_f32_e32 v112, v72
	v_exp_f32_e32 v130, v56
	v_add_f32_e32 v166, v111, v166
	v_add_f32_e32 v167, v129, v167
	v_exp_f32_e32 v113, v73
	v_exp_f32_e32 v131, v57
	v_add_f32_e32 v166, v112, v166
	v_add_f32_e32 v167, v130, v167
	v_exp_f32_e32 v116, v74
	v_exp_f32_e32 v132, v58
	v_add_f32_e32 v166, v113, v166
	v_add_f32_e32 v167, v131, v167
	v_exp_f32_e32 v117, v75
	v_exp_f32_e32 v133, v59
	v_add_f32_e32 v166, v116, v166
	v_add_f32_e32 v167, v132, v167
	v_exp_f32_e32 v118, v76
	v_exp_f32_e32 v134, v60
	v_add_f32_e32 v166, v117, v166
	v_add_f32_e32 v167, v133, v167
	v_exp_f32_e32 v119, v77
	v_exp_f32_e32 v135, v61
	v_add_f32_e32 v166, v118, v166
	v_add_f32_e32 v167, v134, v167
	v_exp_f32_e32 v120, v78
	v_exp_f32_e32 v136, v62
	v_add_f32_e32 v166, v119, v166
	v_add_f32_e32 v167, v135, v167
	v_exp_f32_e32 v121, v79
	v_exp_f32_e32 v137, v63
	v_add_f32_e32 v166, v120, v166
	v_add_f32_e32 v167, v136, v167
	v_exp_f32_e32 v122, v80
	v_exp_f32_e32 v138, v64
	v_add_f32_e32 v166, v121, v166
	v_add_f32_e32 v167, v137, v167
	v_exp_f32_e32 v123, v81
	v_exp_f32_e32 v139, v65
	v_add_f32_e32 v166, v122, v166
	v_add_f32_e32 v167, v138, v167
	s_nop 0
	v_add_f32_e32 v166, v123, v166
	v_add_f32_e32 v167, v139, v167
	v_add_f32_e32 v141, v166, v167
	v_cmp_lt_f32_e32 vcc, s85, v141
	s_cbranch_vccnz .Lfb_s_slow
; __device__ __forceinline__ unsigned cvtpk(float lo, float hi) { f32x2 v = {lo, hi}; bf16x2_t b = __builtin_convertvector(v, bf16x2_t); return __builtin_bit_cast(unsigned, b); }
; template <bool DIFF>
; __device__ __forceinline__ void attn_unit(const AttnP& A, int b, int h, int qi, ldsp lds) {
;     ...
;             bf16x8 pw[4];
; #pragma unroll
;             for (int j = 0; j < 4; ++j) {
;                 u32x4 pk;
;                 if (j < 2) { const int rb = 8 * (j & 1); pk.x = cvtpk(s0[rb], s0[rb + 1]); pk.y = cvtpk(s0[rb + 2], s0[rb + 3]); pk.z = cvtpk(s0[rb + 4], s0[rb + 5]); pk.w = cvtpk(s0[rb + 6], s0[rb + 7]); }
;                 else { const int rb = 8 * (j & 1); pk.x = cvtpk(s1[rb], s1[rb + 1]); pk.y = cvtpk(s1[rb + 2], s1[rb + 3]); pk.z = cvtpk(s1[rb + 4], s1[rb + 5]); pk.w = cvtpk(s1[rb + 6], s1[rb + 7]); }
;                 pw[j] = __builtin_bit_cast(bf16x8, pk);
;             }
;             __builtin_amdgcn_sched_barrier(0);
;             __builtin_amdgcn_s_setprio(1);
; #pragma unroll
;             for (int t = 0; t < 2; ++t)
; #pragma unroll
;                 for (int j = 0; j < 4; ++j) {
;                     const bf16x8 vf = (bf16x8){vlo[t * 4 + j][0], vlo[t * 4 + j][1], vlo[t * 4 + j][2], vlo[t * 4 + j][3], vhi[t * 4 + j][0], vhi[t * 4 + j][1], vhi[t * 4 + j][2], vhi[t * 4 + j][3]};
;                     o[t] = __builtin_amdgcn_mfma_f32_32x32x16_bf16(vf, pw[j], o[t], 0, 0, 0);
;                 }
	v_add_u32_e32 v169, s74, v150
	v_add_u32_e32 v0, s74, v164
	v_add_u32_e32 v168, s75, v161
	ds_read_b64_tr_b16 v[58:59], v168 offset:9216
	ds_read_b64_tr_b16 v[60:61], v168 offset:10752
	ds_read_b64_tr_b16 v[62:63], v168 offset:9280
	ds_read_b64_tr_b16 v[64:65], v168 offset:10816
	ds_read_b64_tr_b16 v[74:75], v168 offset:12288
	ds_read_b64_tr_b16 v[76:77], v168 offset:13824
	ds_read_b64_tr_b16 v[78:79], v168 offset:12352
	ds_read_b64_tr_b16 v[80:81], v168 offset:13888
	ds_read_b64_tr_b16 v[244:245], v168 offset:15360
	ds_read_b64_tr_b16 v[246:247], v168 offset:16896
	v_cvt_pk_bf16_f32 v66, v106, v107
	v_cvt_pk_bf16_f32 v67, v108, v109
	v_cvt_pk_bf16_f32 v68, v110, v111
	v_cvt_pk_bf16_f32 v69, v112, v113
	v_cvt_pk_bf16_f32 v70, v116, v117
	v_cvt_pk_bf16_f32 v71, v118, v119
	v_cvt_pk_bf16_f32 v72, v120, v121
	v_cvt_pk_bf16_f32 v73, v122, v123
	v_cvt_pk_bf16_f32 v50, v124, v125
	v_cvt_pk_bf16_f32 v51, v126, v127
	v_cvt_pk_bf16_f32 v52, v128, v129
	v_cvt_pk_bf16_f32 v53, v130, v131
	v_cvt_pk_bf16_f32 v54, v132, v133
	v_cvt_pk_bf16_f32 v55, v134, v135
	v_cvt_pk_bf16_f32 v56, v136, v137
	v_cvt_pk_bf16_f32 v57, v138, v139
	v_add_f32_e32 v154, v141, v154
	ds_read_b64_tr_b16 v[106:107], v168 offset:15424
	ds_read_b64_tr_b16 v[108:109], v168 offset:16960
	ds_read_b64_tr_b16 v[110:111], v168 offset:18432
	ds_read_b64_tr_b16 v[112:113], v168 offset:19968
	ds_read_b64_tr_b16 v[116:117], v168 offset:18496
	ds_read_b64_tr_b16 v[118:119], v168 offset:20032
	v_mov_b32_e32 v248, s97
	ds_read_b32 v248, v248
	ds_read_b128 v[120:123], v169
	ds_read_b128 v[124:127], v169 offset:4608
	ds_read_b128 v[128:131], v169 offset:32
	ds_read_b128 v[132:135], v169 offset:4640
	ds_read_b128 v[136:139], v169 offset:64
	ds_read_b128 v[170:173], v169 offset:4672
	s_waitcnt lgkmcnt(15)
	v_mfma_f32_32x32x16_bf16 v[18:33], v[58:61], v[66:69], v[18:33]
	v_mfma_f32_32x32x16_bf16 v[2:17], v[62:65], v[66:69], v[2:17]
	v_mfma_f32_32x32x16_bf16 v[18:33], v[74:77], v[70:73], v[18:33]
	v_mfma_f32_32x32x16_bf16 v[2:17], v[78:81], v[70:73], v[2:17]
	s_waitcnt lgkmcnt(13)
	v_mfma_f32_32x32x16_bf16 v[18:33], v[244:247], v[50:53], v[18:33]
	ds_read_b128 v[244:247], v169 offset:96
	s_waitcnt lgkmcnt(12)
	v_mfma_f32_32x32x16_bf16 v[2:17], v[106:109], v[50:53], v[2:17]
	ds_read_b128 v[106:109], v169 offset:4704
	s_waitcnt lgkmcnt(11)
	v_mfma_f32_32x32x16_bf16 v[18:33], v[110:113], v[54:57], v[18:33]
	ds_read_b128 v[110:113], v0 offset:128
	s_waitcnt lgkmcnt(10)
	v_mfma_f32_32x32x16_bf16 v[2:17], v[116:119], v[54:57], v[2:17]
	ds_read_b128 v[116:119], v0 offset:4736
	s_waitcnt lgkmcnt(9)
	v_mfma_f32_32x32x16_bf16 v[66:81], v[120:123], v[90:93], v[34:49]
	s_waitcnt lgkmcnt(8)
	v_mfma_f32_32x32x16_bf16 v[50:65], v[124:127], v[90:93], v[34:49]
	v_sub_f32_e32 v249, v160, v248
	v_cvt_pk_bf16_f32 v162, v249, 0
	v_lshlrev_b32_e32 v162, 16, v162
	s_waitcnt lgkmcnt(7)
	v_mfma_f32_32x32x16_bf16 v[66:81], v[128:131], v[82:85], v[66:81]
	s_waitcnt lgkmcnt(6)
	v_mfma_f32_32x32x16_bf16 v[50:65], v[132:135], v[82:85], v[50:65]
	v_sub_f32_e32 v249, v249, v162
	v_cvt_pk_bf16_f32 v163, v249, 0
	v_and_b32_e32 v157, 0xffff, v163
	v_lshlrev_b32_e32 v163, 16, v163
	s_waitcnt lgkmcnt(5)
	v_mfma_f32_32x32x16_bf16 v[66:81], v[136:139], v[86:89], v[66:81]
	s_waitcnt lgkmcnt(4)
	v_mfma_f32_32x32x16_bf16 v[50:65], v[170:173], v[86:89], v[50:65]
	v_sub_f32_e32 v249, v249, v163
	v_cvt_pk_bf16_f32 v249, v249, 0
	v_or_b32_e32 v162, 0x3f80, v162
	v_lshl_or_b32 v249, v249, 16, v157
	v_cndmask_b32_e64 v140, 0, v114, s[46:47]
	v_cndmask_b32_e64 v142, 0, v249, s[46:47]
	v_cndmask_b32_e64 v141, 0, v162, s[46:47]
	v_mov_b32_e32 v143, v1
	s_waitcnt lgkmcnt(3)
	v_mfma_f32_32x32x16_bf16 v[66:81], v[244:247], v[94:97], v[66:81]
	s_waitcnt lgkmcnt(2)
	v_mfma_f32_32x32x16_bf16 v[50:65], v[106:109], v[94:97], v[50:65]
	s_waitcnt lgkmcnt(1)
	v_mfma_f32_32x32x16_bf16 v[66:81], v[110:113], v[140:143], v[66:81]
	s_waitcnt lgkmcnt(0)
	v_mfma_f32_32x32x16_bf16 v[50:65], v[116:119], v[140:143], v[50:65]
	s_waitcnt vmcnt(0)
	v_add_u32_e32 v115, s75, v156
	ds_write_b128 v115, v[98:101]
	s_and_saveexec_b64 s[0:1], s[44:45]
	v_xor_b32_e32 v248, 0x80000000, v155
	v_cvt_pk_bf16_f32 v248, v248, 0
	v_lshlrev_b32_e32 v249, 16, v248
	v_sub_f32_e64 v249, -v155, v249
	v_cvt_pk_bf16_f32 v162, v249, 0
	v_lshlrev_b32_e32 v162, 16, v162
	v_sub_f32_e32 v249, v249, v162
	v_cvt_pk_bf16_f32 v249, v249, 0
	v_and_or_b32 v112, v248, s83, v162
	v_and_or_b32 v113, v249, s83, 1.0
	v_mov_b32_e32 v115, v1
	v_add_u32_e32 v248, s75, v159
	ds_write_b128 v248, v[112:115] offset:128
	s_mov_b64 exec, s[0:1]
	v_add_u32_e32 v115, s74, v158
	ds_write_b128 v115, v[102:105] offset:9216
	global_load_dwordx4 v[102:105], v[250:251], off
	v_lshl_add_u64 v[250:251], v[250:251], 0, s[26:27]
	global_load_dwordx4 v[98:101], v[152:153], off
	v_lshl_add_u64 v[152:153], v[152:153], 0, s[26:27]
	s_and_saveexec_b64 s[0:1], s[44:45]
	global_load_dword v155, v[252:253], off
	s_mov_b64 exec, s[0:1]
	s_mov_b64 s[0:1], 0x800
	v_lshl_add_u64 v[252:253], v[252:253], 0, s[0:1]
	s_waitcnt lgkmcnt(0)
	s_barrier
	s_add_i32 s99, s99, 1
	s_add_i32 s94, s94, 1
	s_add_i32 s97, s97, 4
	s_add_i32 s98, s98, 64
	s_add_i32 s0, s95, 0
	s_cmp_le_i32 s99, s0
	s_cbranch_scc1 .Lfb_s_top
